# in-projection and up-projection GEMMs: first K-loop iteration peeled with zero C operands, the 128-register accumulator clear before every unit removed
# baseline (speedup 1.0000x reference)
.LBB0_80:
	s_ashr_i32 s65, s64, 31
	s_lshl_b64 s[50:51], s[64:65], 19
	s_add_u32 s90, s34, s50
	s_addc_u32 s91, s35, s51
	s_and_b64 s[6:7], s[6:7], exec
	s_cselect_b32 s9, s91, s49
	s_cselect_b32 s65, s90, s48
	s_add_u32 vcc_lo, s48, 0x100
	s_addc_u32 vcc_hi, s49, 0
	s_mov_b32 s86, -2
	s_add_u32 s6, s10, 0x100
	s_addc_u32 s7, s11, 0
	s_add_i32 s80, 0, 0x10000
	s_cmp_eq_u32 s86, 12
	s_cselect_b32 s51, s67, s7
	s_cselect_b32 s50, s66, s6
	s_cselect_b32 s49, s9, vcc_hi
	s_cselect_b32 s48, s65, vcc_lo
	s_add_i32 s58, 0, 0x14000
	s_waitcnt vmcnt(0)
	v_add_u32_e32 v58, s80, v241
	v_add_u32_e32 v82, s58, v241
	ds_read_b128 v[42:45], v58
	ds_read_b128 v[46:49], v58 offset:1024
	ds_read_b128 v[50:53], v58 offset:2048
	ds_read_b128 v[58:61], v58 offset:3072
	ds_read_b128 v[70:73], v82
	ds_read_b128 v[74:77], v82 offset:1024
	ds_read_b128 v[78:81], v82 offset:2048
	ds_read_b128 v[82:85], v82 offset:3072
	v_lshl_add_u64 v[204:205], s[10:11], 0, v[202:203]
	s_add_i32 m0, s40, 0xc000
	ds_read_b128 v[98:101], v242
	ds_read_b128 v[122:125], v242 offset:1024
	ds_read_b128 v[134:137], v242 offset:2048
	ds_read_b128 v[174:177], v242 offset:3072
	ds_read_b128 v[178:181], v242 offset:4096
	ds_read_b128 v[182:185], v242 offset:5120
	ds_read_b128 v[186:189], v242 offset:6144
	ds_read_b128 v[190:193], v242 offset:7168
	global_load_lds_dwordx4 v[204:205], off
	v_lshl_add_u64 v[204:205], s[10:11], 0, v[222:223]
	s_add_i32 m0, s40, 0xe000
	s_nop 0
	global_load_lds_dwordx4 v[204:205], off
	s_waitcnt vmcnt(8)
	s_waitcnt lgkmcnt(0)
	s_barrier
	s_setprio 1
	s_waitcnt lgkmcnt(0)
	v_mfma_f32_16x16x32_bf16 v[170:173], v[42:45], v[98:101], 0
	v_mfma_f32_16x16x32_bf16 v[166:169], v[50:53], v[98:101], 0
	v_mfma_f32_16x16x32_bf16 v[154:157], v[42:45], v[134:137], 0
	v_mfma_f32_16x16x32_bf16 v[150:153], v[50:53], v[134:137], 0
	v_mfma_f32_16x16x32_bf16 v[138:141], v[42:45], v[178:181], 0
	v_mfma_f32_16x16x32_bf16 v[130:133], v[50:53], v[178:181], 0
	v_mfma_f32_16x16x32_bf16 v[118:121], v[42:45], v[186:189], 0
	v_mfma_f32_16x16x32_bf16 v[110:113], v[50:53], v[186:189], 0
	v_mfma_f32_16x16x32_bf16 v[170:173], v[46:49], v[122:125], v[170:173]
	v_mfma_f32_16x16x32_bf16 v[166:169], v[58:61], v[122:125], v[166:169]
	v_mfma_f32_16x16x32_bf16 v[154:157], v[46:49], v[174:177], v[154:157]
	v_mfma_f32_16x16x32_bf16 v[150:153], v[58:61], v[174:177], v[150:153]
	v_mfma_f32_16x16x32_bf16 v[138:141], v[46:49], v[182:185], v[138:141]
	v_mfma_f32_16x16x32_bf16 v[130:133], v[58:61], v[182:185], v[130:133]
	v_mfma_f32_16x16x32_bf16 v[118:121], v[46:49], v[190:193], v[118:121]
	v_mfma_f32_16x16x32_bf16 v[110:113], v[58:61], v[190:193], v[110:113]
	s_setprio 0
	s_setprio 1
	v_mfma_f32_16x16x32_bf16 v[158:161], v[70:73], v[98:101], 0
	v_mfma_f32_16x16x32_bf16 v[98:101], v[78:81], v[98:101], 0
	v_mfma_f32_16x16x32_bf16 v[114:117], v[70:73], v[178:181], 0
	v_mfma_f32_16x16x32_bf16 v[126:129], v[78:81], v[178:181], 0
	v_mfma_f32_16x16x32_bf16 v[102:105], v[70:73], v[186:189], 0
	v_mfma_f32_16x16x32_bf16 v[106:109], v[78:81], v[186:189], 0
	v_mfma_f32_16x16x32_bf16 v[158:161], v[74:77], v[122:125], v[158:161]
	v_mfma_f32_16x16x32_bf16 v[98:101], v[82:85], v[122:125], v[98:101]
	v_mfma_f32_16x16x32_bf16 v[122:125], v[70:73], v[134:137], 0
	v_mfma_f32_16x16x32_bf16 v[134:137], v[78:81], v[134:137], 0
	v_mfma_f32_16x16x32_bf16 v[114:117], v[74:77], v[182:185], v[114:117]
	v_mfma_f32_16x16x32_bf16 v[126:129], v[82:85], v[182:185], v[126:129]
	v_mfma_f32_16x16x32_bf16 v[102:105], v[74:77], v[190:193], v[102:105]
	v_mfma_f32_16x16x32_bf16 v[106:109], v[82:85], v[190:193], v[106:109]
	v_mfma_f32_16x16x32_bf16 v[122:125], v[74:77], v[174:177], v[122:125]
	v_mfma_f32_16x16x32_bf16 v[134:137], v[82:85], v[174:177], v[134:137]
	s_setprio 0
	s_barrier
	s_add_i32 s10, s80, s37
	v_lshl_add_u64 v[208:209], s[48:49], 0, v[196:197]
	s_mov_b32 m0, s10
	ds_read_b128 v[142:145], v242 offset:16384
	ds_read_b128 v[146:149], v242 offset:17408
	ds_read_b128 v[162:165], v242 offset:18432
	ds_read_b128 v[174:177], v242 offset:19456
	ds_read_b128 v[178:181], v242 offset:20480
	ds_read_b128 v[182:185], v242 offset:21504
	ds_read_b128 v[186:189], v242 offset:22528
	ds_read_b128 v[190:193], v242 offset:23552
	global_load_lds_dwordx4 v[208:209], off
	s_add_i32 m0, s10, 0x2000
	s_add_u32 s10, s48, 0x40000
	v_lshl_add_u64 v[210:211], s[48:49], 0, v[200:201]
	s_addc_u32 s11, s49, 0
	s_add_i32 s58, s58, s37
	global_load_lds_dwordx4 v[210:211], off
	v_lshl_add_u64 v[204:205], s[10:11], 0, v[196:197]
	s_mov_b32 m0, s58
	v_lshl_add_u64 v[212:213], s[50:51], 0, v[194:195]
	global_load_lds_dwordx4 v[204:205], off
	v_lshl_add_u64 v[204:205], s[10:11], 0, v[200:201]
	s_add_i32 m0, s58, 0x2000
	v_lshl_add_u64 v[214:215], s[50:51], 0, v[198:199]
	global_load_lds_dwordx4 v[204:205], off
	s_mov_b32 m0, s40
	s_nop 0
	global_load_lds_dwordx4 v[212:213], off
	s_mov_b32 m0, s57
	s_nop 0
	global_load_lds_dwordx4 v[214:215], off
	s_waitcnt vmcnt(8)
	s_waitcnt lgkmcnt(0)
	s_barrier
	s_setprio 1
	s_waitcnt lgkmcnt(0)
	v_mfma_f32_16x16x32_bf16 v[94:97], v[42:45], v[142:145], 0
	v_mfma_f32_16x16x32_bf16 v[90:93], v[50:53], v[142:145], 0
	v_mfma_f32_16x16x32_bf16 v[62:65], v[42:45], v[162:165], 0
	v_mfma_f32_16x16x32_bf16 v[54:57], v[50:53], v[162:165], 0
	v_mfma_f32_16x16x32_bf16 v[30:33], v[42:45], v[178:181], 0
	v_mfma_f32_16x16x32_bf16 v[26:29], v[50:53], v[178:181], 0
	v_mfma_f32_16x16x32_bf16 v[18:21], v[42:45], v[186:189], 0
	v_mfma_f32_16x16x32_bf16 v[10:13], v[50:53], v[186:189], 0
	v_mfma_f32_16x16x32_bf16 v[94:97], v[46:49], v[146:149], v[94:97]
	v_mfma_f32_16x16x32_bf16 v[90:93], v[58:61], v[146:149], v[90:93]
	v_mfma_f32_16x16x32_bf16 v[62:65], v[46:49], v[174:177], v[62:65]
	v_mfma_f32_16x16x32_bf16 v[54:57], v[58:61], v[174:177], v[54:57]
	v_mfma_f32_16x16x32_bf16 v[30:33], v[46:49], v[182:185], v[30:33]
	v_mfma_f32_16x16x32_bf16 v[26:29], v[58:61], v[182:185], v[26:29]
	v_mfma_f32_16x16x32_bf16 v[18:21], v[46:49], v[190:193], v[18:21]
	v_mfma_f32_16x16x32_bf16 v[10:13], v[58:61], v[190:193], v[10:13]
	s_setprio 0
	s_setprio 1
	v_mfma_f32_16x16x32_bf16 v[34:37], v[70:73], v[162:165], 0
	v_mfma_f32_16x16x32_bf16 v[38:41], v[78:81], v[162:165], 0
	v_mfma_f32_16x16x32_bf16 v[14:17], v[70:73], v[178:181], 0
	v_mfma_f32_16x16x32_bf16 v[22:25], v[78:81], v[178:181], 0
	v_mfma_f32_16x16x32_bf16 v[2:5], v[70:73], v[186:189], 0
	v_mfma_f32_16x16x32_bf16 v[6:9], v[78:81], v[186:189], 0
	v_mfma_f32_16x16x32_bf16 v[42:45], v[70:73], v[142:145], 0
	v_mfma_f32_16x16x32_bf16 v[46:49], v[78:81], v[142:145], 0
	v_mfma_f32_16x16x32_bf16 v[34:37], v[74:77], v[174:177], v[34:37]
	v_mfma_f32_16x16x32_bf16 v[38:41], v[82:85], v[174:177], v[38:41]
	v_mfma_f32_16x16x32_bf16 v[14:17], v[74:77], v[182:185], v[14:17]
	v_mfma_f32_16x16x32_bf16 v[22:25], v[82:85], v[182:185], v[22:25]
	v_mfma_f32_16x16x32_bf16 v[2:5], v[74:77], v[190:193], v[2:5]
	v_mfma_f32_16x16x32_bf16 v[6:9], v[82:85], v[190:193], v[6:9]
	v_mfma_f32_16x16x32_bf16 v[42:45], v[74:77], v[146:149], v[42:45]
	v_mfma_f32_16x16x32_bf16 v[46:49], v[82:85], v[146:149], v[46:49]
	s_setprio 0
	s_barrier
	s_add_i32 s58, 0, 0x18000
	s_add_i32 s80, 0, 0x1c000
	v_add_u32_e32 v70, s58, v241
	v_add_u32_e32 v86, s80, v241
	ds_read_b128 v[50:53], v70
	ds_read_b128 v[58:61], v70 offset:1024
	ds_read_b128 v[66:69], v70 offset:2048
	ds_read_b128 v[70:73], v70 offset:3072
	ds_read_b128 v[74:77], v86
	ds_read_b128 v[78:81], v86 offset:1024
	ds_read_b128 v[82:85], v86 offset:2048
	ds_read_b128 v[174:177], v86 offset:3072
	s_add_u32 s10, s50, 0x40000
	s_addc_u32 s11, s51, 0
	s_mov_b32 m0, s74
	v_lshl_add_u64 v[162:163], s[10:11], 0, v[194:195]
	ds_read_b128 v[86:89], v242 offset:32768
	ds_read_b128 v[142:145], v242 offset:33792
	ds_read_b128 v[146:149], v242 offset:34816
	ds_read_b128 v[178:181], v242 offset:35840
	ds_read_b128 v[182:185], v242 offset:36864
	ds_read_b128 v[186:189], v242 offset:37888
	ds_read_b128 v[190:193], v242 offset:38912
	ds_read_b128 v[204:207], v242 offset:39936
	global_load_lds_dwordx4 v[162:163], off
	v_lshl_add_u64 v[162:163], s[10:11], 0, v[198:199]
	s_mov_b32 m0, s75
	s_nop 0
	global_load_lds_dwordx4 v[162:163], off
	s_waitcnt vmcnt(8)
	s_waitcnt lgkmcnt(0)
	s_barrier
	s_setprio 1
	s_waitcnt lgkmcnt(0)
	v_mfma_f32_16x16x32_bf16 v[162:165], v[50:53], v[86:89], v[170:173]
	v_mfma_f32_16x16x32_bf16 v[170:173], v[58:61], v[142:145], v[162:165]
	v_mfma_f32_16x16x32_bf16 v[162:165], v[66:69], v[86:89], v[166:169]
	v_mfma_f32_16x16x32_bf16 v[154:157], v[50:53], v[146:149], v[154:157]
	v_mfma_f32_16x16x32_bf16 v[150:153], v[66:69], v[146:149], v[150:153]
	v_mfma_f32_16x16x32_bf16 v[138:141], v[50:53], v[182:185], v[138:141]
	v_mfma_f32_16x16x32_bf16 v[130:133], v[66:69], v[182:185], v[130:133]
	v_mfma_f32_16x16x32_bf16 v[118:121], v[50:53], v[190:193], v[118:121]
	v_mfma_f32_16x16x32_bf16 v[110:113], v[66:69], v[190:193], v[110:113]
	v_mfma_f32_16x16x32_bf16 v[166:169], v[70:73], v[142:145], v[162:165]
	v_mfma_f32_16x16x32_bf16 v[154:157], v[58:61], v[178:181], v[154:157]
	v_mfma_f32_16x16x32_bf16 v[150:153], v[70:73], v[178:181], v[150:153]
	v_mfma_f32_16x16x32_bf16 v[138:141], v[58:61], v[186:189], v[138:141]
	v_mfma_f32_16x16x32_bf16 v[130:133], v[70:73], v[186:189], v[130:133]
	v_mfma_f32_16x16x32_bf16 v[118:121], v[58:61], v[204:207], v[118:121]
	v_mfma_f32_16x16x32_bf16 v[110:113], v[70:73], v[204:207], v[110:113]
	s_setprio 0
	s_setprio 1
	v_mfma_f32_16x16x32_bf16 v[158:161], v[74:77], v[86:89], v[158:161]
	v_mfma_f32_16x16x32_bf16 v[86:89], v[82:85], v[86:89], v[98:101]
	v_mfma_f32_16x16x32_bf16 v[162:165], v[174:177], v[142:145], v[86:89]
	v_mfma_f32_16x16x32_bf16 v[86:89], v[74:77], v[146:149], v[122:125]
	v_mfma_f32_16x16x32_bf16 v[158:161], v[78:81], v[142:145], v[158:161]
	v_mfma_f32_16x16x32_bf16 v[142:145], v[78:81], v[178:181], v[86:89]
	v_mfma_f32_16x16x32_bf16 v[86:89], v[82:85], v[146:149], v[134:137]
	v_mfma_f32_16x16x32_bf16 v[146:149], v[174:177], v[178:181], v[86:89]
	v_mfma_f32_16x16x32_bf16 v[86:89], v[74:77], v[182:185], v[114:117]
	v_mfma_f32_16x16x32_bf16 v[114:117], v[78:81], v[186:189], v[86:89]
	v_mfma_f32_16x16x32_bf16 v[86:89], v[82:85], v[182:185], v[126:129]
	v_mfma_f32_16x16x32_bf16 v[126:129], v[174:177], v[186:189], v[86:89]
	v_mfma_f32_16x16x32_bf16 v[86:89], v[74:77], v[190:193], v[102:105]
	v_mfma_f32_16x16x32_bf16 v[102:105], v[78:81], v[204:207], v[86:89]
	v_mfma_f32_16x16x32_bf16 v[86:89], v[82:85], v[190:193], v[106:109]
	v_mfma_f32_16x16x32_bf16 v[106:109], v[174:177], v[204:207], v[86:89]
	s_setprio 0
	s_barrier
	s_add_i32 s10, s58, s37
	v_lshl_add_u64 v[204:205], v[208:209], 0, s[42:43]
	s_mov_b32 m0, s10
	s_nop 1
	ds_read_b128 v[86:89], v242 offset:49152
	ds_read_b128 v[98:101], v242 offset:50176
	ds_read_b128 v[122:125], v242 offset:51200
	ds_read_b128 v[134:137], v242 offset:52224
	ds_read_b128 v[178:181], v242 offset:53248
	ds_read_b128 v[182:185], v242 offset:54272
	ds_read_b128 v[186:189], v242 offset:55296
	ds_read_b128 v[190:193], v242 offset:56320
	global_load_lds_dwordx4 v[204:205], off
	s_add_i32 m0, s10, 0x2000
	s_add_u32 s10, s48, 0x40080
	v_lshl_add_u64 v[204:205], v[210:211], 0, s[42:43]
	s_addc_u32 s11, s49, 0
	s_add_i32 s48, s80, s37
	global_load_lds_dwordx4 v[204:205], off
	v_lshl_add_u64 v[204:205], s[10:11], 0, v[196:197]
	s_mov_b32 m0, s48
	s_nop 0
	global_load_lds_dwordx4 v[204:205], off
	v_lshl_add_u64 v[204:205], s[10:11], 0, v[200:201]
	s_add_i32 m0, s48, 0x2000
	s_nop 0
	global_load_lds_dwordx4 v[204:205], off
	v_lshl_add_u64 v[204:205], v[212:213], 0, s[42:43]
	s_mov_b32 m0, s93
	s_nop 0
	global_load_lds_dwordx4 v[204:205], off
	v_lshl_add_u64 v[204:205], v[214:215], 0, s[42:43]
	s_mov_b32 m0, s94
	s_nop 0
	global_load_lds_dwordx4 v[204:205], off
	s_waitcnt vmcnt(8)
	s_waitcnt lgkmcnt(0)
	s_barrier
	s_setprio 1
	s_waitcnt lgkmcnt(0)
	v_mfma_f32_16x16x32_bf16 v[94:97], v[50:53], v[86:89], v[94:97]
	v_mfma_f32_16x16x32_bf16 v[90:93], v[66:69], v[86:89], v[90:93]
	v_mfma_f32_16x16x32_bf16 v[62:65], v[50:53], v[122:125], v[62:65]
	v_mfma_f32_16x16x32_bf16 v[54:57], v[66:69], v[122:125], v[54:57]
	v_mfma_f32_16x16x32_bf16 v[30:33], v[50:53], v[178:181], v[30:33]
	v_mfma_f32_16x16x32_bf16 v[26:29], v[66:69], v[178:181], v[26:29]
	v_mfma_f32_16x16x32_bf16 v[18:21], v[50:53], v[186:189], v[18:21]
	v_mfma_f32_16x16x32_bf16 v[10:13], v[66:69], v[186:189], v[10:13]
	v_mfma_f32_16x16x32_bf16 v[94:97], v[58:61], v[98:101], v[94:97]
	v_mfma_f32_16x16x32_bf16 v[90:93], v[70:73], v[98:101], v[90:93]
	v_mfma_f32_16x16x32_bf16 v[62:65], v[58:61], v[134:137], v[62:65]
	v_mfma_f32_16x16x32_bf16 v[54:57], v[70:73], v[134:137], v[54:57]
	v_mfma_f32_16x16x32_bf16 v[30:33], v[58:61], v[182:185], v[30:33]
	v_mfma_f32_16x16x32_bf16 v[26:29], v[70:73], v[182:185], v[26:29]
	v_mfma_f32_16x16x32_bf16 v[18:21], v[58:61], v[190:193], v[18:21]
	v_mfma_f32_16x16x32_bf16 v[10:13], v[70:73], v[190:193], v[10:13]
	s_setprio 0
	s_setprio 1
	v_mfma_f32_16x16x32_bf16 v[42:45], v[74:77], v[86:89], v[42:45]
	v_mfma_f32_16x16x32_bf16 v[66:69], v[78:81], v[98:101], v[42:45]
	v_mfma_f32_16x16x32_bf16 v[42:45], v[82:85], v[86:89], v[46:49]
	v_mfma_f32_16x16x32_bf16 v[34:37], v[74:77], v[122:125], v[34:37]
	v_mfma_f32_16x16x32_bf16 v[38:41], v[82:85], v[122:125], v[38:41]
	v_mfma_f32_16x16x32_bf16 v[14:17], v[74:77], v[178:181], v[14:17]
	v_mfma_f32_16x16x32_bf16 v[22:25], v[82:85], v[178:181], v[22:25]
	v_mfma_f32_16x16x32_bf16 v[2:5], v[74:77], v[186:189], v[2:5]
	v_mfma_f32_16x16x32_bf16 v[6:9], v[82:85], v[186:189], v[6:9]
	v_mfma_f32_16x16x32_bf16 v[86:89], v[174:177], v[98:101], v[42:45]
	v_mfma_f32_16x16x32_bf16 v[34:37], v[78:81], v[134:137], v[34:37]
	v_mfma_f32_16x16x32_bf16 v[38:41], v[174:177], v[134:137], v[38:41]
	v_mfma_f32_16x16x32_bf16 v[14:17], v[78:81], v[182:185], v[14:17]
	v_mfma_f32_16x16x32_bf16 v[22:25], v[174:177], v[182:185], v[22:25]
	v_mfma_f32_16x16x32_bf16 v[2:5], v[78:81], v[190:193], v[2:5]
	v_mfma_f32_16x16x32_bf16 v[6:9], v[174:177], v[190:193], v[6:9]
	s_setprio 0
	s_barrier
	s_add_i32 s86, s86, 2
	s_add_u32 vcc_lo, vcc_lo, 0x100
	s_addc_u32 vcc_hi, vcc_hi, 0
	s_cmp_gt_u32 s86, 13
	s_mov_b64 s[10:11], s[6:7]
	s_cbranch_scc0 .LBB0_81
	s_branch .Lpeel_exit_k0

.Lpeel_exit_k0:
	s_mul_i32 s48, s36, 0xfe
	v_mov_b32_e32 v42, v1
	s_add_i32 s6, s95, s48
	v_mov_b32_e32 v49, 0x3fff
	v_add_u32_e32 v46, s6, v42
	v_add_u32_e32 v43, 16, v46
	v_med3_i32 v42, v46, 0, v49
	v_med3_i32 v43, v43, 0, v49
	v_lshlrev_b32_e32 v42, 4, v42
	v_lshlrev_b32_e32 v43, 4, v43
	global_load_dwordx4 v[182:185], v42, s[18:19]
	global_load_dwordx4 v[178:181], v43, s[18:19]
	v_add_u32_e32 v42, 32, v46
	v_add_u32_e32 v43, 48, v46
	v_add_u32_e32 v47, 0x80, v46
	v_med3_i32 v42, v42, 0, v49
	v_med3_i32 v43, v43, 0, v49
	v_med3_i32 v47, v47, 0, v49
	v_add_u32_e32 v48, 0x90, v46
	v_lshlrev_b32_e32 v42, 4, v42
	v_lshlrev_b32_e32 v43, 4, v43
	v_lshlrev_b32_e32 v47, 4, v47
	v_med3_i32 v48, v48, 0, v49
	global_load_dwordx4 v[174:177], v42, s[18:19]
	s_nop 0
	global_load_dwordx4 v[42:45], v43, s[18:19]
	v_lshlrev_b32_e32 v48, 4, v48
	global_load_dwordx4 v[134:137], v47, s[18:19]
	global_load_dwordx4 v[122:125], v48, s[18:19]
	v_add_u32_e32 v47, 0xa0, v46
	v_add_u32_e32 v46, 0xb0, v46
	v_med3_i32 v47, v47, 0, v49
	v_med3_i32 v46, v46, 0, v49
	v_lshlrev_b32_e32 v47, 4, v47
	v_lshlrev_b32_e32 v46, 4, v46
	global_load_dwordx4 v[98:101], v47, s[18:19]
	s_nop 0
	global_load_dwordx4 v[46:49], v46, s[18:19]
	s_and_b64 vcc, exec, s[26:27]
	s_cbranch_vccz .LBB0_84
	s_barrier

.LBB0_592:
	s_ashr_i32 s61, s60, 31
	s_lshl_b64 s[0:1], s[60:61], 19
	s_add_u32 s48, s38, s0
	s_addc_u32 s49, s39, s1
	s_and_b64 s[0:1], s[6:7], exec
	s_cselect_b32 s0, s49, s47
	s_cselect_b32 s1, s48, s46
	s_ashr_i32 s67, s66, 31
	s_lshl_b64 s[8:9], s[66:67], 19
	s_add_u32 s50, s78, s8
	s_addc_u32 s51, s79, s9
	s_and_b64 s[8:9], s[6:7], exec
	s_cselect_b32 s34, s51, s65
	s_cselect_b32 s35, s50, s64
	s_add_u32 s36, s64, 0x100
	s_addc_u32 s37, s65, 0
	s_mov_b32 s40, -2
	s_waitcnt vmcnt(0)
	s_add_u32 s8, s46, 0x100
	s_addc_u32 s9, s47, 0
	s_add_i32 s52, 0, 0x10000
	s_cmp_eq_u32 s40, 12
	s_cselect_b32 vcc_hi, s0, s9
	s_cselect_b32 vcc_lo, s1, s8
	s_cselect_b32 s65, s34, s37
	s_cselect_b32 s64, s35, s36
	s_add_i32 s53, 0, 0x14000
	v_add_u32_e32 v142, s52, v203
	v_add_u32_e32 v158, s53, v203
	ds_read_b128 v[130:133], v142
	ds_read_b128 v[134:137], v142 offset:1024
	ds_read_b128 v[138:141], v142 offset:2048
	ds_read_b128 v[142:145], v142 offset:3072
	ds_read_b128 v[146:149], v158
	ds_read_b128 v[150:153], v158 offset:1024
	ds_read_b128 v[154:157], v158 offset:2048
	ds_read_b128 v[158:161], v158 offset:3072
	v_lshl_add_u64 v[204:205], s[46:47], 0, v[170:171]
	s_add_i32 m0, s19, 0xc000
	ds_read_b128 v[174:177], v222
	ds_read_b128 v[178:181], v222 offset:1024
	ds_read_b128 v[182:185], v222 offset:2048
	ds_read_b128 v[186:189], v222 offset:3072
	ds_read_b128 v[190:193], v222 offset:4096
	ds_read_b128 v[194:197], v222 offset:5120
	ds_read_b128 v[198:201], v222 offset:6144
	ds_read_b128 v[240:243], v222 offset:7168
	global_load_lds_dwordx4 v[204:205], off
	v_lshl_add_u64 v[204:205], s[46:47], 0, v[172:173]
	s_add_i32 m0, s19, 0xe000
	s_nop 0
	global_load_lds_dwordx4 v[204:205], off
	s_waitcnt vmcnt(8)
	s_waitcnt lgkmcnt(0)
	s_barrier
	s_setprio 1
	s_waitcnt lgkmcnt(0)
	v_mfma_f32_16x16x32_bf16 v[126:129], v[130:133], v[174:177], 0
	v_mfma_f32_16x16x32_bf16 v[122:125], v[138:141], v[174:177], 0
	v_mfma_f32_16x16x32_bf16 v[110:113], v[130:133], v[182:185], 0
	v_mfma_f32_16x16x32_bf16 v[106:109], v[138:141], v[182:185], 0
	v_mfma_f32_16x16x32_bf16 v[94:97], v[130:133], v[190:193], 0
	v_mfma_f32_16x16x32_bf16 v[90:93], v[138:141], v[190:193], 0
	v_mfma_f32_16x16x32_bf16 v[78:81], v[130:133], v[198:201], 0
	v_mfma_f32_16x16x32_bf16 v[74:77], v[138:141], v[198:201], 0
	v_mfma_f32_16x16x32_bf16 v[126:129], v[134:137], v[178:181], v[126:129]
	v_mfma_f32_16x16x32_bf16 v[122:125], v[142:145], v[178:181], v[122:125]
	v_mfma_f32_16x16x32_bf16 v[110:113], v[134:137], v[186:189], v[110:113]
	v_mfma_f32_16x16x32_bf16 v[106:109], v[142:145], v[186:189], v[106:109]
	v_mfma_f32_16x16x32_bf16 v[94:97], v[134:137], v[194:197], v[94:97]
	v_mfma_f32_16x16x32_bf16 v[90:93], v[142:145], v[194:197], v[90:93]
	v_mfma_f32_16x16x32_bf16 v[78:81], v[134:137], v[240:243], v[78:81]
	v_mfma_f32_16x16x32_bf16 v[74:77], v[142:145], v[240:243], v[74:77]
	s_setprio 0
	s_setprio 1
	v_mfma_f32_16x16x32_bf16 v[118:121], v[146:149], v[174:177], 0
	v_mfma_f32_16x16x32_bf16 v[114:117], v[154:157], v[174:177], 0
	v_mfma_f32_16x16x32_bf16 v[102:105], v[146:149], v[182:185], 0
	v_mfma_f32_16x16x32_bf16 v[98:101], v[154:157], v[182:185], 0
	v_mfma_f32_16x16x32_bf16 v[86:89], v[146:149], v[190:193], 0
	v_mfma_f32_16x16x32_bf16 v[82:85], v[154:157], v[190:193], 0
	v_mfma_f32_16x16x32_bf16 v[70:73], v[146:149], v[198:201], 0
	v_mfma_f32_16x16x32_bf16 v[66:69], v[154:157], v[198:201], 0
	v_mfma_f32_16x16x32_bf16 v[118:121], v[150:153], v[178:181], v[118:121]
	v_mfma_f32_16x16x32_bf16 v[114:117], v[158:161], v[178:181], v[114:117]
	v_mfma_f32_16x16x32_bf16 v[102:105], v[150:153], v[186:189], v[102:105]
	v_mfma_f32_16x16x32_bf16 v[98:101], v[158:161], v[186:189], v[98:101]
	v_mfma_f32_16x16x32_bf16 v[86:89], v[150:153], v[194:197], v[86:89]
	v_mfma_f32_16x16x32_bf16 v[82:85], v[158:161], v[194:197], v[82:85]
	v_mfma_f32_16x16x32_bf16 v[70:73], v[150:153], v[240:243], v[70:73]
	v_mfma_f32_16x16x32_bf16 v[66:69], v[158:161], v[240:243], v[66:69]
	s_setprio 0
	s_barrier
	s_add_i32 s46, s52, s18
	v_lshl_add_u64 v[204:205], s[64:65], 0, v[164:165]
	s_mov_b32 m0, s46
	ds_read_b128 v[174:177], v222 offset:16384
	ds_read_b128 v[178:181], v222 offset:17408
	ds_read_b128 v[182:185], v222 offset:18432
	ds_read_b128 v[186:189], v222 offset:19456
	ds_read_b128 v[190:193], v222 offset:20480
	ds_read_b128 v[194:197], v222 offset:21504
	ds_read_b128 v[198:201], v222 offset:22528
	ds_read_b128 v[240:243], v222 offset:23552
	global_load_lds_dwordx4 v[204:205], off
	s_add_i32 m0, s46, 0x2000
	s_add_u32 s46, s64, 0x40000
	v_lshl_add_u64 v[206:207], s[64:65], 0, v[168:169]
	s_addc_u32 s47, s65, 0
	s_add_i32 s52, s53, s18
	global_load_lds_dwordx4 v[206:207], off
	v_lshl_add_u64 v[208:209], s[46:47], 0, v[164:165]
	s_mov_b32 m0, s52
	v_lshl_add_u64 v[210:211], vcc, 0, v[166:167]
	global_load_lds_dwordx4 v[208:209], off
	v_lshl_add_u64 v[208:209], s[46:47], 0, v[168:169]
	s_add_i32 m0, s52, 0x2000
	s_nop 0
	global_load_lds_dwordx4 v[208:209], off
	v_lshl_add_u64 v[208:209], vcc, 0, v[162:163]
	s_mov_b32 m0, s19
	s_nop 0
	global_load_lds_dwordx4 v[208:209], off
	s_mov_b32 m0, s45
	s_nop 0
	global_load_lds_dwordx4 v[210:211], off
	s_waitcnt vmcnt(8)
	s_waitcnt lgkmcnt(0)
	s_barrier
	s_setprio 1
	s_waitcnt lgkmcnt(0)
	v_mfma_f32_16x16x32_bf16 v[62:65], v[130:133], v[174:177], 0
	v_mfma_f32_16x16x32_bf16 v[58:61], v[138:141], v[174:177], 0
	v_mfma_f32_16x16x32_bf16 v[46:49], v[130:133], v[182:185], 0
	v_mfma_f32_16x16x32_bf16 v[42:45], v[138:141], v[182:185], 0
	v_mfma_f32_16x16x32_bf16 v[30:33], v[130:133], v[190:193], 0
	v_mfma_f32_16x16x32_bf16 v[26:29], v[138:141], v[190:193], 0
	v_mfma_f32_16x16x32_bf16 v[14:17], v[130:133], v[198:201], 0
	v_mfma_f32_16x16x32_bf16 v[10:13], v[138:141], v[198:201], 0
	v_mfma_f32_16x16x32_bf16 v[62:65], v[134:137], v[178:181], v[62:65]
	v_mfma_f32_16x16x32_bf16 v[58:61], v[142:145], v[178:181], v[58:61]
	v_mfma_f32_16x16x32_bf16 v[46:49], v[134:137], v[186:189], v[46:49]
	v_mfma_f32_16x16x32_bf16 v[42:45], v[142:145], v[186:189], v[42:45]
	v_mfma_f32_16x16x32_bf16 v[30:33], v[134:137], v[194:197], v[30:33]
	v_mfma_f32_16x16x32_bf16 v[26:29], v[142:145], v[194:197], v[26:29]
	v_mfma_f32_16x16x32_bf16 v[14:17], v[134:137], v[240:243], v[14:17]
	v_mfma_f32_16x16x32_bf16 v[10:13], v[142:145], v[240:243], v[10:13]
	s_setprio 0
	s_setprio 1
	v_mfma_f32_16x16x32_bf16 v[54:57], v[146:149], v[174:177], 0
	v_mfma_f32_16x16x32_bf16 v[50:53], v[154:157], v[174:177], 0
	v_mfma_f32_16x16x32_bf16 v[38:41], v[146:149], v[182:185], 0
	v_mfma_f32_16x16x32_bf16 v[34:37], v[154:157], v[182:185], 0
	v_mfma_f32_16x16x32_bf16 v[22:25], v[146:149], v[190:193], 0
	v_mfma_f32_16x16x32_bf16 v[18:21], v[154:157], v[190:193], 0
	v_mfma_f32_16x16x32_bf16 v[6:9], v[146:149], v[198:201], 0
	v_mfma_f32_16x16x32_bf16 v[2:5], v[154:157], v[198:201], 0
	v_mfma_f32_16x16x32_bf16 v[54:57], v[150:153], v[178:181], v[54:57]
	v_mfma_f32_16x16x32_bf16 v[50:53], v[158:161], v[178:181], v[50:53]
	v_mfma_f32_16x16x32_bf16 v[38:41], v[150:153], v[186:189], v[38:41]
	v_mfma_f32_16x16x32_bf16 v[34:37], v[158:161], v[186:189], v[34:37]
	v_mfma_f32_16x16x32_bf16 v[22:25], v[150:153], v[194:197], v[22:25]
	v_mfma_f32_16x16x32_bf16 v[18:21], v[158:161], v[194:197], v[18:21]
	v_mfma_f32_16x16x32_bf16 v[6:9], v[150:153], v[240:243], v[6:9]
	v_mfma_f32_16x16x32_bf16 v[2:5], v[158:161], v[240:243], v[2:5]
	s_setprio 0
	s_barrier
	s_add_i32 s52, 0, 0x18000
	s_add_i32 s53, 0, 0x1c000
	v_add_u32_e32 v142, s52, v203
	v_add_u32_e32 v158, s53, v203
	ds_read_b128 v[130:133], v142
	ds_read_b128 v[134:137], v142 offset:1024
	ds_read_b128 v[138:141], v142 offset:2048
	ds_read_b128 v[142:145], v142 offset:3072
	ds_read_b128 v[146:149], v158
	ds_read_b128 v[150:153], v158 offset:1024
	ds_read_b128 v[154:157], v158 offset:2048
	ds_read_b128 v[158:161], v158 offset:3072
	s_add_u32 s46, vcc_lo, 0x40000
	s_addc_u32 s47, vcc_hi, 0
	s_mov_b32 m0, s16
	v_lshl_add_u64 v[214:215], s[46:47], 0, v[162:163]
	ds_read_b128 v[174:177], v222 offset:32768
	ds_read_b128 v[178:181], v222 offset:33792
	ds_read_b128 v[182:185], v222 offset:34816
	ds_read_b128 v[186:189], v222 offset:35840
	ds_read_b128 v[190:193], v222 offset:36864
	ds_read_b128 v[194:197], v222 offset:37888
	ds_read_b128 v[198:201], v222 offset:38912
	ds_read_b128 v[240:243], v222 offset:39936
	global_load_lds_dwordx4 v[214:215], off
	v_lshl_add_u64 v[214:215], s[46:47], 0, v[166:167]
	s_mov_b32 m0, s17
	s_nop 0
	global_load_lds_dwordx4 v[214:215], off
	s_waitcnt vmcnt(8)
	s_waitcnt lgkmcnt(0)
	s_barrier
	s_setprio 1
	s_waitcnt lgkmcnt(0)
	v_mfma_f32_16x16x32_bf16 v[126:129], v[130:133], v[174:177], v[126:129]
	v_mfma_f32_16x16x32_bf16 v[122:125], v[138:141], v[174:177], v[122:125]
	v_mfma_f32_16x16x32_bf16 v[110:113], v[130:133], v[182:185], v[110:113]
	v_mfma_f32_16x16x32_bf16 v[106:109], v[138:141], v[182:185], v[106:109]
	v_mfma_f32_16x16x32_bf16 v[94:97], v[130:133], v[190:193], v[94:97]
	v_mfma_f32_16x16x32_bf16 v[90:93], v[138:141], v[190:193], v[90:93]
	v_mfma_f32_16x16x32_bf16 v[78:81], v[130:133], v[198:201], v[78:81]
	v_mfma_f32_16x16x32_bf16 v[74:77], v[138:141], v[198:201], v[74:77]
	v_mfma_f32_16x16x32_bf16 v[126:129], v[134:137], v[178:181], v[126:129]
	v_mfma_f32_16x16x32_bf16 v[122:125], v[142:145], v[178:181], v[122:125]
	v_mfma_f32_16x16x32_bf16 v[110:113], v[134:137], v[186:189], v[110:113]
	v_mfma_f32_16x16x32_bf16 v[106:109], v[142:145], v[186:189], v[106:109]
	v_mfma_f32_16x16x32_bf16 v[94:97], v[134:137], v[194:197], v[94:97]
	v_mfma_f32_16x16x32_bf16 v[90:93], v[142:145], v[194:197], v[90:93]
	v_mfma_f32_16x16x32_bf16 v[78:81], v[134:137], v[240:243], v[78:81]
	v_mfma_f32_16x16x32_bf16 v[74:77], v[142:145], v[240:243], v[74:77]
	s_setprio 0
	s_setprio 1
	v_mfma_f32_16x16x32_bf16 v[118:121], v[146:149], v[174:177], v[118:121]
	v_mfma_f32_16x16x32_bf16 v[114:117], v[154:157], v[174:177], v[114:117]
	v_mfma_f32_16x16x32_bf16 v[102:105], v[146:149], v[182:185], v[102:105]
	v_mfma_f32_16x16x32_bf16 v[98:101], v[154:157], v[182:185], v[98:101]
	v_mfma_f32_16x16x32_bf16 v[86:89], v[146:149], v[190:193], v[86:89]
	v_mfma_f32_16x16x32_bf16 v[82:85], v[154:157], v[190:193], v[82:85]
	v_mfma_f32_16x16x32_bf16 v[70:73], v[146:149], v[198:201], v[70:73]
	v_mfma_f32_16x16x32_bf16 v[66:69], v[154:157], v[198:201], v[66:69]
	v_mfma_f32_16x16x32_bf16 v[118:121], v[150:153], v[178:181], v[118:121]
	v_mfma_f32_16x16x32_bf16 v[114:117], v[158:161], v[178:181], v[114:117]
	v_mfma_f32_16x16x32_bf16 v[102:105], v[150:153], v[186:189], v[102:105]
	v_mfma_f32_16x16x32_bf16 v[98:101], v[158:161], v[186:189], v[98:101]
	v_mfma_f32_16x16x32_bf16 v[86:89], v[150:153], v[194:197], v[86:89]
	v_mfma_f32_16x16x32_bf16 v[82:85], v[158:161], v[194:197], v[82:85]
	v_mfma_f32_16x16x32_bf16 v[70:73], v[150:153], v[240:243], v[70:73]
	v_mfma_f32_16x16x32_bf16 v[66:69], v[158:161], v[240:243], v[66:69]
	s_setprio 0
	s_barrier
	s_add_i32 s46, s52, s18
	v_lshl_add_u64 v[204:205], v[204:205], 0, s[42:43]
	s_mov_b32 m0, s46
	ds_read_b128 v[174:177], v222 offset:49152
	ds_read_b128 v[178:181], v222 offset:50176
	ds_read_b128 v[182:185], v222 offset:51200
	ds_read_b128 v[186:189], v222 offset:52224
	ds_read_b128 v[190:193], v222 offset:53248
	ds_read_b128 v[194:197], v222 offset:54272
	ds_read_b128 v[198:201], v222 offset:55296
	ds_read_b128 v[240:243], v222 offset:56320
	global_load_lds_dwordx4 v[204:205], off
	s_add_i32 m0, s46, 0x2000
	s_add_u32 s46, s64, 0x40080
	v_lshl_add_u64 v[204:205], v[206:207], 0, s[42:43]
	s_addc_u32 s47, s65, 0
	s_add_i32 s52, s53, s18
	global_load_lds_dwordx4 v[204:205], off
	v_lshl_add_u64 v[204:205], s[46:47], 0, v[164:165]
	s_mov_b32 m0, s52
	s_nop 0
	global_load_lds_dwordx4 v[204:205], off
	v_lshl_add_u64 v[204:205], s[46:47], 0, v[168:169]
	s_add_i32 m0, s52, 0x2000
	s_nop 0
	global_load_lds_dwordx4 v[204:205], off
	v_lshl_add_u64 v[204:205], v[208:209], 0, s[42:43]
	s_mov_b32 m0, s4
	s_nop 0
	global_load_lds_dwordx4 v[204:205], off
	v_lshl_add_u64 v[204:205], v[210:211], 0, s[42:43]
	s_mov_b32 m0, s5
	s_nop 0
	global_load_lds_dwordx4 v[204:205], off
	s_waitcnt vmcnt(8)
	s_waitcnt lgkmcnt(0)
	s_barrier
	s_setprio 1
	s_waitcnt lgkmcnt(0)
	v_mfma_f32_16x16x32_bf16 v[62:65], v[130:133], v[174:177], v[62:65]
	v_mfma_f32_16x16x32_bf16 v[58:61], v[138:141], v[174:177], v[58:61]
	v_mfma_f32_16x16x32_bf16 v[46:49], v[130:133], v[182:185], v[46:49]
	v_mfma_f32_16x16x32_bf16 v[42:45], v[138:141], v[182:185], v[42:45]
	v_mfma_f32_16x16x32_bf16 v[30:33], v[130:133], v[190:193], v[30:33]
	v_mfma_f32_16x16x32_bf16 v[26:29], v[138:141], v[190:193], v[26:29]
	v_mfma_f32_16x16x32_bf16 v[14:17], v[130:133], v[198:201], v[14:17]
	v_mfma_f32_16x16x32_bf16 v[10:13], v[138:141], v[198:201], v[10:13]
	v_mfma_f32_16x16x32_bf16 v[62:65], v[134:137], v[178:181], v[62:65]
	v_mfma_f32_16x16x32_bf16 v[58:61], v[142:145], v[178:181], v[58:61]
	v_mfma_f32_16x16x32_bf16 v[46:49], v[134:137], v[186:189], v[46:49]
	v_mfma_f32_16x16x32_bf16 v[42:45], v[142:145], v[186:189], v[42:45]
	v_mfma_f32_16x16x32_bf16 v[30:33], v[134:137], v[194:197], v[30:33]
	v_mfma_f32_16x16x32_bf16 v[26:29], v[142:145], v[194:197], v[26:29]
	v_mfma_f32_16x16x32_bf16 v[14:17], v[134:137], v[240:243], v[14:17]
	v_mfma_f32_16x16x32_bf16 v[10:13], v[142:145], v[240:243], v[10:13]
	s_setprio 0
	s_setprio 1
	v_mfma_f32_16x16x32_bf16 v[54:57], v[146:149], v[174:177], v[54:57]
	v_mfma_f32_16x16x32_bf16 v[50:53], v[154:157], v[174:177], v[50:53]
	v_mfma_f32_16x16x32_bf16 v[38:41], v[146:149], v[182:185], v[38:41]
	v_mfma_f32_16x16x32_bf16 v[34:37], v[154:157], v[182:185], v[34:37]
	v_mfma_f32_16x16x32_bf16 v[22:25], v[146:149], v[190:193], v[22:25]
	v_mfma_f32_16x16x32_bf16 v[18:21], v[154:157], v[190:193], v[18:21]
	v_mfma_f32_16x16x32_bf16 v[6:9], v[146:149], v[198:201], v[6:9]
	v_mfma_f32_16x16x32_bf16 v[2:5], v[154:157], v[198:201], v[2:5]
	v_mfma_f32_16x16x32_bf16 v[54:57], v[150:153], v[178:181], v[54:57]
	v_mfma_f32_16x16x32_bf16 v[50:53], v[158:161], v[178:181], v[50:53]
	v_mfma_f32_16x16x32_bf16 v[38:41], v[150:153], v[186:189], v[38:41]
	v_mfma_f32_16x16x32_bf16 v[34:37], v[158:161], v[186:189], v[34:37]
	v_mfma_f32_16x16x32_bf16 v[22:25], v[150:153], v[194:197], v[22:25]
	v_mfma_f32_16x16x32_bf16 v[18:21], v[158:161], v[194:197], v[18:21]
	v_mfma_f32_16x16x32_bf16 v[6:9], v[150:153], v[240:243], v[6:9]
	v_mfma_f32_16x16x32_bf16 v[2:5], v[158:161], v[240:243], v[2:5]
	s_setprio 0
	s_barrier
	s_add_i32 s40, s40, 2
	s_add_u32 s36, s36, 0x100
	s_addc_u32 s37, s37, 0
	s_cmp_gt_u32 s40, 13
	s_mov_b64 s[46:47], s[8:9]
	s_cbranch_scc0 .LBB0_593
	s_branch .Lpeel_exit_k1

.Lpeel_exit_k1:
	v_mov_b32_e32 v130, v1
	s_lshl_b32 s47, s74, 8
	s_add_i32 s46, s47, s27
	v_add_u32_e32 v130, s46, v130
	v_add_u32_e32 v134, 16, v130
	v_ashrrev_i32_e32 v131, 31, v130
	v_ashrrev_i32_e32 v135, 31, v134
	v_lshl_add_u64 v[132:133], v[130:131], 4, s[94:95]
	v_lshl_add_u64 v[134:135], v[134:135], 4, s[94:95]
	global_load_dwordx4 v[158:161], v[132:133], off
	global_load_dwordx4 v[150:153], v[134:135], off
	v_add_u32_e32 v132, 32, v130
	v_add_u32_e32 v134, 48, v130
	v_ashrrev_i32_e32 v133, 31, v132
	v_ashrrev_i32_e32 v135, 31, v134
	v_lshl_add_u64 v[132:133], v[132:133], 4, s[94:95]
	v_lshl_add_u64 v[134:135], v[134:135], 4, s[94:95]
	global_load_dwordx4 v[154:157], v[132:133], off
	global_load_dwordx4 v[142:145], v[134:135], off
	v_add_u32_e32 v132, 0x80, v130
	v_add_u32_e32 v134, 0x90, v130
	v_ashrrev_i32_e32 v133, 31, v132
	v_ashrrev_i32_e32 v135, 31, v134
	v_lshl_add_u64 v[132:133], v[132:133], 4, s[94:95]
	v_lshl_add_u64 v[134:135], v[134:135], 4, s[94:95]
	global_load_dwordx4 v[146:149], v[132:133], off
	s_nop 0
	global_load_dwordx4 v[134:137], v[134:135], off
	v_add_u32_e32 v132, 0xa0, v130
	v_add_u32_e32 v130, 0xb0, v130
	v_ashrrev_i32_e32 v133, 31, v132
	v_ashrrev_i32_e32 v131, 31, v130
	v_lshl_add_u64 v[132:133], v[132:133], 4, s[94:95]
	v_lshl_add_u64 v[130:131], v[130:131], 4, s[94:95]
	global_load_dwordx4 v[138:141], v[132:133], off
	s_nop 0
	global_load_dwordx4 v[130:133], v[130:131], off
	s_and_b64 vcc, exec, s[20:21]
	s_cbranch_vccz .LBB0_596
	s_barrier
